# attention steps: four redundant add-zero row-sum ops removed (on top of the FFN-in epilogue changes)
# baseline (speedup 1.0000x reference)
.LBB0_334:
	v_add_u32_e32 v83, s44, v232
	v_add_u32_e32 v255, 0xe800, v83
	ds_read_b64_tr_b16 v[84:85], v83 offset:24576
	ds_read_b64_tr_b16 v[86:87], v83 offset:25088
	s_waitcnt lgkmcnt(9)
	v_mfma_f32_32x32x16_bf16 v[66:81], v[174:177], v[2:5], v[66:81]
	v_add_f32_e32 v88, v114, v115
	v_add_f32_e32 v88, v116, v88
	v_add_f32_e32 v88, v117, v88
	v_add_f32_e32 v88, v118, v88
	v_add_f32_e32 v92, v119, v88
	v_cvt_pk_bf16_f32 v142, v114, v115
	v_cvt_pk_bf16_f32 v143, v116, v117
	ds_read_b64_tr_b16 v[88:89], v83 offset:28672
	ds_read_b64_tr_b16 v[90:91], v83 offset:29184
	s_waitcnt lgkmcnt(10)
	v_mfma_f32_32x32x16_bf16 v[50:65], v[170:173], v[2:5], v[50:65]
	v_add_f32_e32 v92, v120, v92
	v_add_f32_e32 v92, v121, v92
	v_add_f32_e32 v92, v122, v92
	v_add_f32_e32 v96, v123, v92
	v_cvt_pk_bf16_f32 v144, v118, v119
	v_cvt_pk_bf16_f32 v145, v120, v121
	ds_read_b64_tr_b16 v[92:93], v83 offset:25600
	ds_read_b64_tr_b16 v[94:95], v83 offset:26112
	s_waitcnt lgkmcnt(11)
	v_mfma_f32_32x32x16_bf16 v[66:81], v[166:169], v[6:9], v[66:81]
	v_add_f32_e32 v96, v124, v96
	v_add_f32_e32 v96, v125, v96
	v_add_f32_e32 v96, v126, v96
	v_add_f32_e32 v96, v127, v96
	v_cvt_pk_bf16_f32 v138, v122, v123
	v_cvt_pk_bf16_f32 v139, v124, v125
	ds_read_b64_tr_b16 v[114:115], v83 offset:29696
	ds_read_b64_tr_b16 v[116:117], v83 offset:30208
	s_waitcnt lgkmcnt(12)
	v_mfma_f32_32x32x16_bf16 v[50:65], v[162:165], v[6:9], v[50:65]
	v_add_f32_e32 v96, v128, v96
	v_add_f32_e32 v96, v129, v96
	v_add_f32_e32 v96, v98, v96
	v_add_f32_e32 v96, v99, v96
	v_cvt_pk_bf16_f32 v140, v126, v127
	v_cvt_pk_bf16_f32 v141, v128, v129
	ds_read_b64_tr_b16 v[118:119], v83 offset:26624
	ds_read_b64_tr_b16 v[120:121], v83 offset:27136
	s_waitcnt lgkmcnt(13)
	v_mfma_f32_32x32x16_bf16 v[66:81], v[158:161], v[10:13], v[66:81]
	v_add_f32_e32 v96, v100, v96
	v_add_f32_e32 v96, v101, v96
	v_add_f32_e32 v96, v102, v96
	v_add_f32_e32 v96, v103, v96
	v_cvt_pk_bf16_f32 v134, v98, v99
	v_cvt_pk_bf16_f32 v135, v100, v101
	ds_read_b64_tr_b16 v[98:99], v83 offset:30720
	ds_read_b64_tr_b16 v[100:101], v83 offset:31232
	s_waitcnt lgkmcnt(14)
	v_mfma_f32_32x32x16_bf16 v[50:65], v[154:157], v[10:13], v[50:65]
	v_add_f32_e32 v96, v104, v96
	v_add_f32_e32 v96, v105, v96
	v_add_f32_e32 v96, v106, v96
	v_add_f32_e32 v96, v107, v96
	v_cvt_pk_bf16_f32 v136, v102, v103
	v_cvt_pk_bf16_f32 v137, v104, v105
	ds_read_b64_tr_b16 v[102:103], v83 offset:27648
	ds_read_b64_tr_b16 v[104:105], v83 offset:28160
	s_waitcnt lgkmcnt(14)
	v_mfma_f32_32x32x16_bf16 v[66:81], v[150:153], v[14:17], v[66:81]
	v_add_f32_e32 v96, v108, v96
	v_add_f32_e32 v96, v109, v96
	v_add_f32_e32 v96, v110, v96
	v_add_f32_e32 v96, v111, v96
	v_cvt_pk_bf16_f32 v130, v106, v107
	v_cvt_pk_bf16_f32 v131, v108, v109
	ds_read_b64_tr_b16 v[106:107], v83 offset:31744
	ds_read_b64_tr_b16 v[108:109], v83 offset:32256
	v_mfma_f32_32x32x16_bf16 v[50:65], v[146:149], v[14:17], v[50:65]
	v_add_f32_e32 v83, v112, v96
	v_add_f32_e32 v83, v113, v83
	v_cvt_pk_bf16_f32 v132, v110, v111
	v_cvt_pk_bf16_f32 v133, v112, v113
	s_nop 0
	v_add_f32_e32 v166, v82, v83
	s_mov_b64 s[44:45], 0
	s_and_saveexec_b64 s[64:65], s[40:41]
	s_cbranch_execz .LBB0_337
	v_max_f32_e32 v82, v67, v67
	v_max_f32_e32 v83, v66, v66
	v_max_f32_e32 v82, v83, v82
	v_max3_f32 v83, v68, v69, v51
	v_max3_f32 v82, v82, v50, v52
	v_max3_f32 v82, v82, v53, v70
	v_max3_f32 v83, v83, v72, v73
	v_max3_f32 v82, v82, v71, v54
	v_max3_f32 v83, v83, v56, v57
	v_max3_f32 v82, v82, v55, v74
	v_max3_f32 v83, v83, v76, v77
	v_max3_f32 v82, v82, v75, v58
	v_max3_f32 v83, v83, v60, v61
	v_max3_f32 v82, v82, v59, v78
	v_max3_f32 v83, v83, v80, v81
	v_max3_f32 v82, v82, v79, v62
	v_max3_f32 v83, v83, v64, v65
	v_max3_f32 v82, v82, v63, v83
	v_mov_b32_e32 v83, v82
	s_nop 1
	v_permlane32_swap_b32_e32 v82, v83
	v_max_f32_e32 v83, v83, v83
	v_max_f32_e32 v82, v82, v82
	v_max_f32_e32 v82, v82, v83
	v_cmp_lt_f32_e32 vcc, s84, v82
	s_cbranch_vccnz .LBB0_346

.LBB0_339:
	s_or_b64 exec, exec, s[64:65]
	s_add_i32 s44, s66, 0x2000
	s_cmpk_lg_i32 s66, 0x4000
	s_cselect_b32 s86, s44, 0
	v_add_u32_e32 v167, s51, v232
	v_add_u32_e32 v255, 0xe800, v167
	ds_read_b64_tr_b16 v[150:151], v167 offset:24576
	ds_read_b64_tr_b16 v[152:153], v167 offset:25088
	s_waitcnt lgkmcnt(9)
	v_mfma_f32_32x32x16_bf16 v[114:129], v[162:165], v[2:5], v[114:129]
	v_add_f32_e32 v130, v66, v67
	v_add_f32_e32 v130, v68, v130
	v_add_f32_e32 v130, v69, v130
	v_add_f32_e32 v130, v70, v130
	v_add_f32_e32 v130, v71, v130
	v_cvt_pk_bf16_f32 v142, v66, v67
	v_cvt_pk_bf16_f32 v143, v68, v69
	ds_read_b64_tr_b16 v[66:67], v167 offset:28672
	ds_read_b64_tr_b16 v[68:69], v167 offset:29184
	s_waitcnt lgkmcnt(10)
	v_mfma_f32_32x32x16_bf16 v[98:113], v[158:161], v[2:5], v[98:113]
	v_add_f32_e32 v130, v72, v130
	v_add_f32_e32 v130, v73, v130
	v_add_f32_e32 v130, v74, v130
	v_add_f32_e32 v130, v75, v130
	v_cvt_pk_bf16_f32 v144, v70, v71
	v_cvt_pk_bf16_f32 v145, v72, v73
	ds_read_b64_tr_b16 v[70:71], v167 offset:25600
	ds_read_b64_tr_b16 v[72:73], v167 offset:26112
	s_waitcnt lgkmcnt(11)
	v_mfma_f32_32x32x16_bf16 v[114:129], v[154:157], v[6:9], v[114:129]
	v_add_f32_e32 v130, v76, v130
	v_add_f32_e32 v130, v77, v130
	v_add_f32_e32 v130, v78, v130
	v_add_f32_e32 v130, v79, v130
	v_cvt_pk_bf16_f32 v138, v74, v75
	v_cvt_pk_bf16_f32 v139, v76, v77
	ds_read_b64_tr_b16 v[74:75], v167 offset:29696
	ds_read_b64_tr_b16 v[76:77], v167 offset:30208
	s_waitcnt lgkmcnt(12)
	v_mfma_f32_32x32x16_bf16 v[98:113], v[146:149], v[6:9], v[98:113]
	v_add_f32_e32 v130, v80, v130
	v_add_f32_e32 v130, v81, v130
	v_add_f32_e32 v130, v50, v130
	v_add_f32_e32 v130, v51, v130
	v_cvt_pk_bf16_f32 v140, v78, v79
	v_cvt_pk_bf16_f32 v141, v80, v81
	ds_read_b64_tr_b16 v[78:79], v167 offset:26624
	ds_read_b64_tr_b16 v[80:81], v167 offset:27136
	s_waitcnt lgkmcnt(13)
	v_mfma_f32_32x32x16_bf16 v[114:129], v[94:97], v[10:13], v[114:129]
	v_add_f32_e32 v94, v52, v130
	v_add_f32_e32 v94, v53, v94
	v_add_f32_e32 v94, v54, v94
	v_add_f32_e32 v94, v55, v94
	v_cvt_pk_bf16_f32 v134, v50, v51
	v_cvt_pk_bf16_f32 v135, v52, v53
	ds_read_b64_tr_b16 v[50:51], v167 offset:30720
	ds_read_b64_tr_b16 v[52:53], v167 offset:31232
	s_waitcnt lgkmcnt(14)
	v_mfma_f32_32x32x16_bf16 v[98:113], v[90:93], v[10:13], v[98:113]
	v_add_f32_e32 v90, v56, v94
	v_add_f32_e32 v90, v57, v90
	v_add_f32_e32 v90, v58, v90
	v_add_f32_e32 v90, v59, v90
	v_cvt_pk_bf16_f32 v136, v54, v55
	v_cvt_pk_bf16_f32 v137, v56, v57
	ds_read_b64_tr_b16 v[54:55], v167 offset:27648
	ds_read_b64_tr_b16 v[56:57], v167 offset:28160
	s_waitcnt lgkmcnt(14)
	v_mfma_f32_32x32x16_bf16 v[114:129], v[86:89], v[14:17], v[114:129]
	v_add_f32_e32 v86, v60, v90
	v_add_f32_e32 v86, v61, v86
	v_add_f32_e32 v86, v62, v86
	v_add_f32_e32 v86, v63, v86
	v_cvt_pk_bf16_f32 v130, v58, v59
	v_cvt_pk_bf16_f32 v131, v60, v61
	ds_read_b64_tr_b16 v[58:59], v167 offset:31744
	ds_read_b64_tr_b16 v[60:61], v167 offset:32256
	v_mfma_f32_32x32x16_bf16 v[98:113], v[82:85], v[14:17], v[98:113]
	v_add_f32_e32 v82, v64, v86
	v_add_f32_e32 v82, v65, v82
	v_cvt_pk_bf16_f32 v132, v62, v63
	v_cvt_pk_bf16_f32 v133, v64, v65
	v_add_f32_e32 v82, v166, v82
	s_mov_b64 s[44:45], 0
	s_and_saveexec_b64 s[64:65], s[40:41]
	s_cbranch_execz .LBB0_342
	v_max_f32_e32 v62, v115, v115
	v_max_f32_e32 v63, v114, v114
	v_max_f32_e32 v62, v63, v62
	v_max3_f32 v63, v116, v117, v99
	v_max3_f32 v62, v62, v98, v100
	v_max3_f32 v62, v62, v101, v118
	v_max3_f32 v63, v63, v120, v121
	v_max3_f32 v62, v62, v119, v102
	v_max3_f32 v63, v63, v104, v105
	v_max3_f32 v62, v62, v103, v122
	v_max3_f32 v63, v63, v124, v125
	v_max3_f32 v62, v62, v123, v106
	v_max3_f32 v63, v63, v108, v109
	v_max3_f32 v62, v62, v107, v126
	v_max3_f32 v63, v63, v128, v129
	v_max3_f32 v62, v62, v127, v110
	v_max3_f32 v63, v63, v112, v113
	v_max3_f32 v62, v62, v111, v63
	v_mov_b32_e32 v63, v62
	s_nop 1
	v_permlane32_swap_b32_e32 v62, v63
	v_max_f32_e32 v63, v63, v63
	v_max_f32_e32 v62, v62, v62
	v_max_f32_e32 v62, v62, v63
	v_cmp_lt_f32_e32 vcc, s84, v62
	s_cbranch_vccnz .LBB0_349

.LBB0_434:
	s_or_b64 exec, exec, s[66:67]
	v_add_u32_e32 v96, s86, v232
	v_add_u32_e32 v255, 0xe800, v96
	ds_read_b64_tr_b16 v[92:93], v96 offset:24576
	ds_read_b64_tr_b16 v[94:95], v96 offset:25088
	s_waitcnt lgkmcnt(9)
	v_mfma_f32_32x32x16_bf16 v[114:129], v[174:177], v[2:5], v[114:129]
	v_add_f32_e32 v84, v66, v67
	v_add_f32_e32 v84, v68, v84
	v_add_f32_e32 v84, v69, v84
	v_add_f32_e32 v84, v70, v84
	v_add_f32_e32 v84, v71, v84
	v_cvt_pk_bf16_f32 v142, v66, v67
	v_cvt_pk_bf16_f32 v143, v68, v69
	ds_read_b64_tr_b16 v[88:89], v96 offset:28672
	ds_read_b64_tr_b16 v[90:91], v96 offset:29184
	s_waitcnt lgkmcnt(10)
	v_mfma_f32_32x32x16_bf16 v[98:113], v[170:173], v[2:5], v[98:113]
	v_add_f32_e32 v66, v72, v84
	v_add_f32_e32 v66, v73, v66
	v_add_f32_e32 v66, v74, v66
	v_add_f32_e32 v66, v75, v66
	v_cvt_pk_bf16_f32 v144, v70, v71
	v_cvt_pk_bf16_f32 v145, v72, v73
	ds_read_b64_tr_b16 v[84:85], v96 offset:25600
	ds_read_b64_tr_b16 v[86:87], v96 offset:26112
	s_waitcnt lgkmcnt(11)
	v_mfma_f32_32x32x16_bf16 v[114:129], v[166:169], v[6:9], v[114:129]
	v_add_f32_e32 v66, v76, v66
	v_add_f32_e32 v66, v77, v66
	v_add_f32_e32 v66, v78, v66
	v_add_f32_e32 v66, v79, v66
	v_cvt_pk_bf16_f32 v138, v74, v75
	v_cvt_pk_bf16_f32 v139, v76, v77
	ds_read_b64_tr_b16 v[74:75], v96 offset:29696
	ds_read_b64_tr_b16 v[76:77], v96 offset:30208
	s_waitcnt lgkmcnt(12)
	v_mfma_f32_32x32x16_bf16 v[98:113], v[162:165], v[6:9], v[98:113]
	v_add_f32_e32 v66, v80, v66
	v_add_f32_e32 v66, v81, v66
	v_add_f32_e32 v66, v50, v66
	v_add_f32_e32 v66, v51, v66
	v_cvt_pk_bf16_f32 v140, v78, v79
	v_cvt_pk_bf16_f32 v141, v80, v81
	ds_read_b64_tr_b16 v[70:71], v96 offset:26624
	ds_read_b64_tr_b16 v[72:73], v96 offset:27136
	s_waitcnt lgkmcnt(13)
	v_mfma_f32_32x32x16_bf16 v[114:129], v[158:161], v[10:13], v[114:129]
	v_add_f32_e32 v66, v52, v66
	v_add_f32_e32 v66, v53, v66
	v_add_f32_e32 v66, v54, v66
	v_add_f32_e32 v78, v55, v66
	v_cvt_pk_bf16_f32 v134, v50, v51
	v_cvt_pk_bf16_f32 v135, v52, v53
	ds_read_b64_tr_b16 v[66:67], v96 offset:30720
	ds_read_b64_tr_b16 v[68:69], v96 offset:31232
	s_waitcnt lgkmcnt(14)
	v_mfma_f32_32x32x16_bf16 v[98:113], v[154:157], v[10:13], v[98:113]
	v_add_f32_e32 v50, v56, v78
	v_add_f32_e32 v50, v57, v50
	v_add_f32_e32 v50, v58, v50
	v_add_f32_e32 v50, v59, v50
	v_cvt_pk_bf16_f32 v136, v54, v55
	v_cvt_pk_bf16_f32 v137, v56, v57
	ds_read_b64_tr_b16 v[54:55], v96 offset:27648
	ds_read_b64_tr_b16 v[56:57], v96 offset:28160
	s_waitcnt lgkmcnt(14)
	v_mfma_f32_32x32x16_bf16 v[114:129], v[150:153], v[14:17], v[114:129]
	v_add_f32_e32 v50, v60, v50
	v_add_f32_e32 v50, v61, v50
	v_add_f32_e32 v50, v62, v50
	v_add_f32_e32 v78, v63, v50
	v_cvt_pk_bf16_f32 v130, v58, v59
	v_cvt_pk_bf16_f32 v131, v60, v61
	ds_read_b64_tr_b16 v[50:51], v96 offset:31744
	ds_read_b64_tr_b16 v[52:53], v96 offset:32256
	v_mfma_f32_32x32x16_bf16 v[98:113], v[146:149], v[14:17], v[98:113]
	v_add_f32_e32 v58, v64, v78
	v_add_f32_e32 v58, v65, v58
	v_cvt_pk_bf16_f32 v132, v62, v63
	v_cvt_pk_bf16_f32 v133, v64, v65
	s_add_i32 s81, s70, 2
	s_cmp_ge_i32 s81, s4
	s_cselect_b64 s[66:67], -1, 0
	s_and_b64 vcc, exec, s[66:67]
	s_cbranch_vccnz .LBB0_436
	s_add_i32 s44, s87, s50
	s_mov_b32 s45, m0
	s_mov_b32 m0, s44
	s_nop 0
	global_load_lds_dwordx4 v[194:195], off
	s_mov_b32 m0, s45

; __device__ __forceinline__ void gmask(f32x16&p0,f32x16&p1,int kvb,int qrel,int hi,bool WIN){
;   const float NEG=-INFINITY; int kb=kvb+4*hi;
;   #pragma unroll
;   for(int r=0;r<16;++r){int kv=kb+(r&3)+8*(r>>2); if(kv>qrel)p0[r]=NEG; if(kv+32>qrel)p1[r]=NEG;
;     if(WIN){ if(kv<=qrel-128)p0[r]=NEG; if(kv+32<=qrel-128)p1[r]=NEG; } }
; }
.LBB0_540:
	v_add_u32_e32 v83, s87, v232
	v_add_u32_e32 v255, 0xe800, v83
	ds_read_b64_tr_b16 v[84:85], v83 offset:24576
	ds_read_b64_tr_b16 v[86:87], v83 offset:25088
	s_waitcnt lgkmcnt(9)
	v_mfma_f32_32x32x16_bf16 v[66:81], v[174:177], v[2:5], v[66:81]
	v_add_f32_e32 v88, v114, v115
	v_add_f32_e32 v88, v116, v88
	v_add_f32_e32 v88, v117, v88
	v_add_f32_e32 v88, v118, v88
	v_add_f32_e32 v92, v119, v88
	v_cvt_pk_bf16_f32 v142, v114, v115
	v_cvt_pk_bf16_f32 v143, v116, v117
	ds_read_b64_tr_b16 v[88:89], v83 offset:28672
	ds_read_b64_tr_b16 v[90:91], v83 offset:29184
	s_waitcnt lgkmcnt(10)
	v_mfma_f32_32x32x16_bf16 v[50:65], v[170:173], v[2:5], v[50:65]
	v_add_f32_e32 v92, v120, v92
	v_add_f32_e32 v92, v121, v92
	v_add_f32_e32 v92, v122, v92
	v_add_f32_e32 v96, v123, v92
	v_cvt_pk_bf16_f32 v144, v118, v119
	v_cvt_pk_bf16_f32 v145, v120, v121
	ds_read_b64_tr_b16 v[92:93], v83 offset:25600
	ds_read_b64_tr_b16 v[94:95], v83 offset:26112
	s_waitcnt lgkmcnt(11)
	v_mfma_f32_32x32x16_bf16 v[66:81], v[166:169], v[6:9], v[66:81]
	v_add_f32_e32 v96, v124, v96
	v_add_f32_e32 v96, v125, v96
	v_add_f32_e32 v96, v126, v96
	v_add_f32_e32 v96, v127, v96
	v_cvt_pk_bf16_f32 v138, v122, v123
	v_cvt_pk_bf16_f32 v139, v124, v125
	ds_read_b64_tr_b16 v[114:115], v83 offset:29696
	ds_read_b64_tr_b16 v[116:117], v83 offset:30208
	s_waitcnt lgkmcnt(12)
	v_mfma_f32_32x32x16_bf16 v[50:65], v[162:165], v[6:9], v[50:65]
	v_add_f32_e32 v96, v128, v96
	v_add_f32_e32 v96, v129, v96
	v_add_f32_e32 v96, v98, v96
	v_add_f32_e32 v96, v99, v96
	v_cvt_pk_bf16_f32 v140, v126, v127
	v_cvt_pk_bf16_f32 v141, v128, v129
	ds_read_b64_tr_b16 v[118:119], v83 offset:26624
	ds_read_b64_tr_b16 v[120:121], v83 offset:27136
	s_waitcnt lgkmcnt(13)
	v_mfma_f32_32x32x16_bf16 v[66:81], v[158:161], v[10:13], v[66:81]
	v_add_f32_e32 v96, v100, v96
	v_add_f32_e32 v96, v101, v96
	v_add_f32_e32 v96, v102, v96
	v_add_f32_e32 v122, v103, v96
	v_cvt_pk_bf16_f32 v134, v98, v99
	v_cvt_pk_bf16_f32 v135, v100, v101
	ds_read_b64_tr_b16 v[96:97], v83 offset:30720
	ds_read_b64_tr_b16 v[98:99], v83 offset:31232
	s_waitcnt lgkmcnt(14)
	v_mfma_f32_32x32x16_bf16 v[50:65], v[154:157], v[10:13], v[50:65]
	v_add_f32_e32 v100, v104, v122
	v_add_f32_e32 v100, v105, v100
	v_add_f32_e32 v100, v106, v100
	v_add_f32_e32 v122, v107, v100
	v_cvt_pk_bf16_f32 v136, v102, v103
	v_cvt_pk_bf16_f32 v137, v104, v105
	ds_read_b64_tr_b16 v[100:101], v83 offset:27648
	ds_read_b64_tr_b16 v[102:103], v83 offset:28160
	s_waitcnt lgkmcnt(14)
	v_mfma_f32_32x32x16_bf16 v[66:81], v[150:153], v[14:17], v[66:81]
	v_add_f32_e32 v104, v108, v122
	v_add_f32_e32 v104, v109, v104
	v_add_f32_e32 v104, v110, v104
	v_add_f32_e32 v122, v111, v104
	v_cvt_pk_bf16_f32 v130, v106, v107
	v_cvt_pk_bf16_f32 v131, v108, v109
	ds_read_b64_tr_b16 v[104:105], v83 offset:31744
	ds_read_b64_tr_b16 v[106:107], v83 offset:32256
	v_mfma_f32_32x32x16_bf16 v[50:65], v[146:149], v[14:17], v[50:65]
	v_add_f32_e32 v83, v112, v122
	v_add_f32_e32 v83, v113, v83
	v_cvt_pk_bf16_f32 v132, v110, v111
	v_cvt_pk_bf16_f32 v133, v112, v113
	s_lshl_b32 s4, s4, 6
	s_sub_i32 s42, s4, 64
	v_or_b32_e32 v108, s42, v230
	v_sub_u32_e32 v108, v223, v108
	s_nop 0
	v_readfirstlane_b32 s43, v108
	s_cmp_gt_i32 s43, 66
	s_cbranch_scc1 .Lmy_mk_c_ls
	v_cmp_le_i32_e32 vcc, 0, v108
	v_cndmask_b32_e32 v66, v217, v66, vcc
	v_cmp_le_i32_e32 vcc, 32, v108
	v_cndmask_b32_e32 v50, v217, v50, vcc
	v_cmp_le_i32_e32 vcc, 1, v108
	v_cndmask_b32_e32 v67, v217, v67, vcc
	v_cmp_le_i32_e32 vcc, 33, v108
	v_cndmask_b32_e32 v51, v217, v51, vcc
	v_cmp_le_i32_e32 vcc, 2, v108
	v_cndmask_b32_e32 v68, v217, v68, vcc
	v_cmp_le_i32_e32 vcc, 34, v108
	v_cndmask_b32_e32 v52, v217, v52, vcc
	v_cmp_le_i32_e32 vcc, 3, v108
	v_cndmask_b32_e32 v69, v217, v69, vcc
	v_cmp_le_i32_e32 vcc, 35, v108
	v_cndmask_b32_e32 v53, v217, v53, vcc
	v_cmp_le_i32_e32 vcc, 8, v108
	v_cndmask_b32_e32 v70, v217, v70, vcc
	v_cmp_le_i32_e32 vcc, 40, v108
	v_cndmask_b32_e32 v54, v217, v54, vcc
	v_cmp_le_i32_e32 vcc, 9, v108
	v_cndmask_b32_e32 v71, v217, v71, vcc
	v_cmp_le_i32_e32 vcc, 41, v108
	v_cndmask_b32_e32 v55, v217, v55, vcc
	v_cmp_le_i32_e32 vcc, 10, v108
	v_cndmask_b32_e32 v72, v217, v72, vcc
	v_cmp_le_i32_e32 vcc, 42, v108
	v_cndmask_b32_e32 v56, v217, v56, vcc
	v_cmp_le_i32_e32 vcc, 11, v108
	v_cndmask_b32_e32 v73, v217, v73, vcc
	v_cmp_le_i32_e32 vcc, 43, v108
	v_cndmask_b32_e32 v57, v217, v57, vcc
	v_cmp_le_i32_e32 vcc, 16, v108
	v_cndmask_b32_e32 v74, v217, v74, vcc
	v_cmp_le_i32_e32 vcc, 48, v108
	v_cndmask_b32_e32 v58, v217, v58, vcc
	v_cmp_le_i32_e32 vcc, 17, v108
	v_cndmask_b32_e32 v75, v217, v75, vcc
	v_cmp_le_i32_e32 vcc, 49, v108
	v_cndmask_b32_e32 v59, v217, v59, vcc
	v_cmp_le_i32_e32 vcc, 18, v108
	v_cndmask_b32_e32 v76, v217, v76, vcc
	v_cmp_le_i32_e32 vcc, 50, v108
	v_cndmask_b32_e32 v60, v217, v60, vcc
	v_cmp_le_i32_e32 vcc, 19, v108
	v_cndmask_b32_e32 v77, v217, v77, vcc
	v_cmp_le_i32_e32 vcc, 51, v108
	v_cndmask_b32_e32 v61, v217, v61, vcc
	v_cmp_le_i32_e32 vcc, 24, v108
	v_cndmask_b32_e32 v78, v217, v78, vcc
	v_cmp_le_i32_e32 vcc, 56, v108
	v_cndmask_b32_e32 v62, v217, v62, vcc
	v_cmp_le_i32_e32 vcc, 25, v108
	v_cndmask_b32_e32 v79, v217, v79, vcc
	v_cmp_le_i32_e32 vcc, 57, v108
	v_cndmask_b32_e32 v63, v217, v63, vcc
	v_cmp_le_i32_e32 vcc, 26, v108
	v_cndmask_b32_e32 v80, v217, v80, vcc
	v_cmp_le_i32_e32 vcc, 58, v108
	v_cndmask_b32_e32 v64, v217, v64, vcc
	v_cmp_le_i32_e32 vcc, 27, v108
	v_cndmask_b32_e32 v81, v217, v81, vcc
	v_cmp_le_i32_e32 vcc, 59, v108
	v_cndmask_b32_e32 v65, v217, v65, vcc
